# step dispatch: per-step (type,arg) looked up from packed immediates with SALU instead of two global_load_ubyte after every grid barrier
# speedup vs baseline: 1.0148x; 1.0148x over previous
; #define LAS __attribute__((address_space(3)))
; #define GAS __attribute__((address_space(1)))
; __global__ void __launch_bounds__(512, 2) hybrid_fwd(Args args) {
;     ...
;     for (int st = 0; st < NSTEPS; ++st) {
;         int tid_o = threadIdx.x; asm volatile("" : "+v"(tid_o));
;         GAS unsigned char* ws1 = (GAS unsigned char*)args.ws; asm volatile("" : "+s"(ws1));
;         GAS float* out1 = (GAS float*)args.out; asm volatile("" : "+s"(out1));
;         unsigned char* ws_g = (unsigned char*)ws1; float* out_g = (float*)out1;
;         unsigned char* ws_f = args.ws; asm volatile("" : "+s"(ws_f));
;         float* out_f = args.out; asm volatile("" : "+s"(out_f));
;         unsigned char* ws = ws_f; float* outp = out_f;
;     ...
;         Ctx c;
;         c.lds = (LAS unsigned char*)lds_raw;
;         c.tid = tid_o; c.lane = c.tid & 63; c.wave = __builtin_amdgcn_readfirstlane(c.tid >> 6);
;         c.G = gridDim.x; c.bid = blockIdx.x; c.gw = c.bid * NWAVES + c.wave; c.ngw = c.G * NWAVES;
;         c.in = args.in; c.out = outp; c.ws = ws; c.dry = st >= NREAL; c.out2 = out_f; c.ws2 = ws_f;
;         const int ty = PROG_T[st], arg = PROG_A[st];
;         switch (ty) {
.LBB0_7:
	v_mov_b32_e32 v164, v163
	s_mov_b64 s[90:91], s[42:43]
	s_mov_b64 s[2:3], s[40:41]
	v_mov_b32_e32 v0, s36
	v_writelane_b32 v254, s2, 8
	v_readfirstlane_b32 s77, v164
	v_and_b32_e32 v162, 63, v164
	v_writelane_b32 v254, s3, 9
	s_mov_b64 s[2:3], s[42:43]
	s_mov_b64 s[2:3], s[40:41]
	s_mov_b64 s[4:5], 0
	v_writelane_b32 v254, s4, 10
	s_ashr_i32 s92, s77, 6
	s_mov_b64 s[2:3], -1
	v_writelane_b32 v254, s5, 11
	s_add_i32 s88, s92, s93
	s_mov_b64 s[78:79], 0
	s_mov_b32 s10, 0xfe03f81
	s_mov_b32 s11, 0x3f317217
	s_mov_b32 s13, 0x40051592
	s_mov_b32 vcc_lo, 0x65243210
	s_mov_b32 vcc_hi, 0x32432987
	s_cmp_lt_u32 s36, 16
	s_cbranch_scc1 .Lprog_t_lo
	s_mov_b32 vcc_lo, 0x432cba24
	s_mov_b32 vcc_hi, 0x2
.Lprog_t_lo:
	s_and_b32 s5, s36, 15
	s_lshl_b32 s5, s5, 2
	s_lshr_b64 vcc, vcc, s5
	s_and_b32 s4, vcc_lo, 15
	s_mov_b32 vcc_lo, 0x100000
	s_mov_b32 vcc_hi, 0x23112000
	s_cmp_lt_u32 s36, 16
	s_cbranch_scc1 .Lprog_a_lo
	s_mov_b32 vcc_lo, 0x33500042
	s_mov_b32 vcc_hi, 0x6
.Lprog_a_lo:
	s_lshr_b64 vcc, vcc, s5
	s_and_b32 s6, vcc_lo, 15
	v_mov_b32_e32 v0, s4
	v_mov_b32_e32 v1, 6
	s_and_b32 s6, s6, 0xff
	v_writelane_b32 v254, s4, 12
	v_cmp_lt_i32_sdwa s[4:5], v0, v1 src0_sel:WORD_0 src1_sel:DWORD
	v_writelane_b32 v254, s6, 13
	s_and_b64 vcc, exec, s[4:5]
	v_writelane_b32 v254, s36, 14
	s_cbranch_vccnz .LBB0_273
	v_readlane_b32 s2, v254, 12
	s_and_b32 s56, 0xffff, s2
	s_cmp_gt_i32 s56, 8
	s_cbranch_scc0 .LBB0_13
	s_cmp_gt_i32 s56, 10
	s_cbranch_scc0 .LBB0_14
	s_cmp_gt_i32 s56, 11
	s_cbranch_scc0 .LBB0_15
	s_mov_b64 s[2:3], 0
	s_cmp_eq_u32 s56, 12
	s_cbranch_scc0 .LBB0_16
	s_add_u32 s4, s90, 0x11388000
	s_addc_u32 s5, s91, 0
	v_writelane_b32 v254, s4, 18
	v_readlane_b32 s16, v251, 63
	v_readlane_b32 s20, v252, 3
	v_writelane_b32 v254, s5, 19
	s_add_u32 s4, s90, 0x6c88000
	s_addc_u32 s5, s91, 0
	v_writelane_b32 v254, s4, 20
	v_readlane_b32 s21, v252, 4
	s_mov_b64 s[78:79], -1
	v_writelane_b32 v254, s5, 21
	v_readlane_b32 s17, v252, 0
	v_readlane_b32 s18, v252, 1
	v_readlane_b32 s19, v252, 2
	v_readlane_b32 s22, v252, 5
	v_readlane_b32 s23, v252, 6
	s_mov_b64 s[38:39], s[20:21]
	s_branch .LBB0_16
